# attention loops: row-max as parallel v_max3 chains, straight branch to exp block, v_pk_add_f32 split into v_add_f32, dead P copies removed (P3)
# speedup vs baseline: 1.0450x; 1.0168x over previous
.LBB0_560:
	s_waitcnt lgkmcnt(6)
	v_mfma_f32_32x32x16_bf16 v[48:63], v[152:155], v[136:139], v[48:63]
	s_xor_b64 s[44:45], s[44:45], -1
	s_waitcnt lgkmcnt(2)
	v_mfma_f32_32x32x16_bf16 v[32:47], v[156:159], v[136:139], v[32:47]
	v_mfma_f32_32x32x16_bf16 v[48:63], v[74:77], v[132:135], v[48:63]
	s_waitcnt lgkmcnt(1)
	v_mfma_f32_32x32x16_bf16 v[32:47], v[144:147], v[132:135], v[32:47]
	v_mfma_f32_32x32x16_bf16 v[48:63], v[70:73], v[128:131], v[48:63]
	ds_read_b128 v[12:15], v192 offset:9216
	ds_read_b128 v[74:77], v192 offset:9248
	ds_read_b128 v[28:31], v192 offset:9280
	ds_read_b128 v[20:23], v192 offset:9312
	ds_read_b128 v[144:147], v192 offset:13824
	ds_read_b128 v[70:73], v192 offset:13856
	ds_read_b128 v[24:27], v192 offset:13888
	ds_read_b128 v[16:19], v192 offset:13920
	s_waitcnt lgkmcnt(8)
	v_mfma_f32_32x32x16_bf16 v[32:47], v[148:151], v[128:131], v[32:47]
	s_nop 1
	v_max_f32_e32 v0, v49, v49
	v_max_f32_e32 v1, v48, v48
	v_max_f32_e32 v0, v1, v0
	v_max3_f32 v0, v0, v50, v51
	v_max3_f32 v2, v52, v53, v54
	v_max3_f32 v0, v0, v55, v56
	v_max3_f32 v2, v2, v57, v58
	v_max3_f32 v0, v0, v59, v60
	v_max3_f32 v2, v2, v61, v62
	v_max3_f32 v0, v0, v63, v2
	v_max3_f32 v1, v32, v33, v34
	v_max3_f32 v2, v35, v36, v37
	v_max3_f32 v3, v38, v39, v40
	v_max3_f32 v1, v1, v41, v42
	v_max3_f32 v2, v2, v43, v44
	v_max3_f32 v3, v3, v45, v46
	v_max3_f32 v1, v1, v2, v3
	v_max3_f32 v0, v0, v1, v47
	v_mov_b32_e32 v1, v0
	s_nop 1
	v_permlane32_swap_b32_e32 v1, v0
	s_and_b64 vcc, exec, s[44:45]
	v_max_f32_e32 v1, v0, v1
	s_cbranch_vccz .LBB0_576
	v_cmp_lt_f32_e32 vcc, s63, v1
	s_mov_b64 s[48:49], 0
	s_mov_b64 s[46:47], 0
	s_cbranch_vccz .LBB0_569
	v_max_f32_e32 v0, v1, v1
	v_max_f32_e32 v0, 0, v0
	s_mov_b64 s[46:47], -1

.LBB0_569:
	v_exp_f32_e32 v0, v48
	v_exp_f32_e32 v148, v49
	v_exp_f32_e32 v2, v50
	v_exp_f32_e32 v150, v51
	v_exp_f32_e32 v4, v52
	v_exp_f32_e32 v152, v53
	v_exp_f32_e32 v6, v54
	v_exp_f32_e32 v154, v55
	v_cvt_pk_bf16_f32 v48, v0, v148
	v_cvt_pk_bf16_f32 v49, v2, v150
	v_cvt_pk_bf16_f32 v50, v4, v152
	v_cvt_pk_bf16_f32 v51, v6, v154
	v_exp_f32_e32 v8, v56
	v_exp_f32_e32 v156, v57
	s_waitcnt lgkmcnt(0)
	v_mfma_f32_32x32x16_bf16 v[96:111], v[12:15], v[48:51], v[96:111]
	v_exp_f32_e32 v10, v58
	v_exp_f32_e32 v158, v59
	v_exp_f32_e32 v12, v60
	v_exp_f32_e32 v160, v61
	v_exp_f32_e32 v14, v62
	v_exp_f32_e32 v162, v63
	v_exp_f32_e32 v1, v32
	v_mfma_f32_32x32x16_bf16 v[80:95], v[144:147], v[48:51], v[80:95]
	v_exp_f32_e32 v149, v33
	v_exp_f32_e32 v3, v34
	v_exp_f32_e32 v151, v35
	v_cvt_pk_bf16_f32 v32, v8, v156
	v_cvt_pk_bf16_f32 v33, v10, v158
	v_cvt_pk_bf16_f32 v34, v12, v160
	v_cvt_pk_bf16_f32 v35, v14, v162
	v_exp_f32_e32 v5, v36
	v_exp_f32_e32 v153, v37
	v_mfma_f32_32x32x16_bf16 v[96:111], v[74:77], v[32:35], v[96:111]
	v_exp_f32_e32 v7, v38
	v_exp_f32_e32 v155, v39
	v_exp_f32_e32 v9, v40
	v_exp_f32_e32 v157, v41
	v_exp_f32_e32 v11, v42
	v_exp_f32_e32 v159, v43
	v_exp_f32_e32 v13, v44
	v_mfma_f32_32x32x16_bf16 v[80:95], v[70:73], v[32:35], v[80:95]
	v_cvt_pk_bf16_f32 v32, v1, v149
	v_cvt_pk_bf16_f32 v33, v3, v151
	v_cvt_pk_bf16_f32 v34, v5, v153
	v_cvt_pk_bf16_f32 v35, v7, v155
	v_exp_f32_e32 v161, v45
	v_exp_f32_e32 v15, v46
	v_exp_f32_e32 v163, v47
	v_mfma_f32_32x32x16_bf16 v[96:111], v[28:31], v[32:35], v[96:111]
	v_add_f32_e64 v28, v0, 0
	v_add_f32_e64 v29, v1, 0
	v_cvt_pk_bf16_f32 v30, v13, v161
	v_add_f32_e64 v28, v148, v28
	v_add_f32_e64 v29, v149, v29
	v_cvt_pk_bf16_f32 v31, v15, v163
	v_add_f32_e32 v28, v2, v28
	v_add_f32_e32 v29, v3, v29
	v_add_f32_e32 v36, v150, v28
	v_add_f32_e32 v37, v151, v29
	v_mfma_f32_32x32x16_bf16 v[80:95], v[24:27], v[32:35], v[80:95]
	v_add_f32_e64 v24, v4, v36
	v_add_f32_e64 v25, v5, v37
	v_cvt_pk_bf16_f32 v28, v9, v157
	v_add_f32_e64 v24, v152, v24
	v_add_f32_e64 v25, v153, v25
	v_cvt_pk_bf16_f32 v29, v11, v159
	v_add_f32_e32 v24, v6, v24
	v_add_f32_e32 v25, v7, v25
	v_add_f32_e32 v24, v154, v24
	v_add_f32_e32 v25, v155, v25
	v_mfma_f32_32x32x16_bf16 v[96:111], v[20:23], v[28:31], v[96:111]
	v_add_f32_e64 v24, v8, v24
	v_add_f32_e64 v25, v9, v25
	v_add_f32_e64 v24, v156, v24
	v_add_f32_e64 v25, v157, v25
	v_add_f32_e32 v20, v10, v24
	v_add_f32_e32 v21, v11, v25
	v_add_f32_e32 v20, v158, v20
	v_add_f32_e32 v21, v159, v21
	v_mfma_f32_32x32x16_bf16 v[80:95], v[16:19], v[28:31], v[80:95]
	v_add_f32_e64 v20, v12, v20
	v_add_f32_e64 v21, v13, v21
	v_add_f32_e64 v20, v160, v20
	v_add_f32_e64 v21, v161, v21
	v_add_f32_e32 v20, v14, v20
	v_add_f32_e32 v21, v15, v21
	v_add_f32_e32 v20, v162, v20
	v_add_f32_e32 v21, v163, v21
	v_add_f32_e32 v20, v20, v21
	v_add_f32_e32 v171, v171, v20
	s_mov_b64 s[44:45], 0
	s_andn2_b64 vcc, exec, s[42:43]
	s_cbranch_vccz .LBB0_571
	s_branch .LBB0_574
.LBB0_570:
	s_andn2_b64 vcc, exec, s[42:43]
	s_cbranch_vccnz .LBB0_574
.LBB0_571:
	s_bitcmp1_b32 s77, 0
	s_cselect_b32 s42, 0x5c00, 0
	s_add_i32 s46, s42, 0
	v_add3_u32 v70, s46, v187, v186
	s_waitcnt vmcnt(0)
	ds_write_b128 v70, v[66:69]
	s_and_saveexec_b64 s[42:43], s[2:3]
	s_cbranch_execz .LBB0_573
	v_add3_u32 v74, s46, v188, v189
	v_perm_b32 v70, v174, v172, s60
	v_perm_b32 v71, v178, v176, s60
	v_perm_b32 v72, v174, v172, s61
	v_perm_b32 v73, v178, v176, s61
	v_add_u32_e32 v74, 0x2000, v74
	ds_write2_b64 v74, v[70:71], v[72:73] offset0:128 offset1:146
	v_perm_b32 v70, v175, v173, s60
	v_perm_b32 v71, v179, v177, s60
	v_perm_b32 v72, v175, v173, s61
	v_perm_b32 v73, v179, v177, s61
	ds_write2_b64 v74, v[70:71], v[72:73] offset0:164 offset1:182

.LBB0_1341:
	s_cmp_gt_i32 s54, s51
	s_cselect_b64 s[48:49], -1, 0
	s_or_b64 s[48:49], s[44:45], s[48:49]
	s_and_b64 vcc, exec, s[48:49]
	s_cbranch_vccnz .LBB0_1350
	s_xor_b64 s[48:49], s[4:5], -1
	s_bitcmp1_b32 s54, 0
	s_cselect_b32 s4, 0x5c00, 0
	s_add_i32 s4, s4, 0
	v_add3_u32 v160, s4, v173, v144
	v_add3_u32 v248, s4, v171, v144
	ds_read_b128 v[48:51], v160
	ds_read_b128 v[124:127], v160 offset:4608
	ds_read_b128 v[112:115], v160 offset:32
	ds_read_b128 v[128:131], v160 offset:4640
	ds_read_b128 v[116:119], v160 offset:64
	ds_read_b128 v[132:135], v160 offset:4672
	ds_read_b128 v[120:123], v160 offset:96
	ds_read_b128 v[136:139], v160 offset:4704
	ds_read_b128 v[194:197], v248 offset:18432
	ds_read_b128 v[202:205], v248 offset:20992
	ds_read_b128 v[198:201], v248 offset:18464
	ds_read_b128 v[206:209], v248 offset:21024
	s_waitcnt lgkmcnt(11)
	v_mfma_f32_32x32x16_bf16 v[64:79], v[48:51], v[100:103], v[0:15]
	s_waitcnt lgkmcnt(10)
	v_mfma_f32_32x32x16_bf16 v[48:63], v[124:127], v[100:103], v[0:15]
	s_waitcnt lgkmcnt(9)
	v_mfma_f32_32x32x16_bf16 v[64:79], v[112:115], v[96:99], v[64:79]
	s_waitcnt lgkmcnt(8)
	v_mfma_f32_32x32x16_bf16 v[48:63], v[128:131], v[96:99], v[48:63]
	s_waitcnt lgkmcnt(7)
	v_mfma_f32_32x32x16_bf16 v[64:79], v[116:119], v[92:95], v[64:79]
	s_waitcnt lgkmcnt(6)
	v_mfma_f32_32x32x16_bf16 v[48:63], v[132:135], v[92:95], v[48:63]
	s_waitcnt lgkmcnt(5)
	v_mfma_f32_32x32x16_bf16 v[64:79], v[120:123], v[88:91], v[64:79]
	s_waitcnt lgkmcnt(4)
	v_mfma_f32_32x32x16_bf16 v[48:63], v[136:139], v[88:91], v[48:63]
	ds_read_b128 v[140:143], v160 offset:9216
	ds_read_b128 v[132:135], v160 offset:9248
	ds_read_b128 v[124:127], v160 offset:9280
	ds_read_b128 v[116:119], v160 offset:9312
	ds_read_b128 v[136:139], v160 offset:13824
	ds_read_b128 v[128:131], v160 offset:13856
	ds_read_b128 v[120:123], v160 offset:13888
	ds_read_b128 v[112:115], v160 offset:13920
	s_waitcnt lgkmcnt(11)
	v_mfma_f32_32x32x16_bf16 v[64:79], v[194:197], v[84:87], v[64:79]
	s_waitcnt lgkmcnt(10)
	v_mfma_f32_32x32x16_bf16 v[48:63], v[202:205], v[84:87], v[48:63]
	s_waitcnt lgkmcnt(9)
	v_mfma_f32_32x32x16_bf16 v[64:79], v[198:201], v[80:83], v[64:79]
	s_waitcnt lgkmcnt(8)
	v_mfma_f32_32x32x16_bf16 v[48:63], v[206:209], v[80:83], v[48:63]
	s_nop 1
	v_max_f32_e32 v160, v65, v65
	v_max_f32_e32 v174, v64, v64
	v_max_f32_e32 v160, v174, v160
	v_max3_f32 v160, v160, v66, v67
	v_max3_f32 v175, v68, v69, v70
	v_max3_f32 v160, v160, v71, v72
	v_max3_f32 v175, v175, v73, v74
	v_max3_f32 v160, v160, v75, v76
	v_max3_f32 v175, v175, v77, v78
	v_max3_f32 v160, v160, v79, v175
	v_max3_f32 v174, v48, v49, v50
	v_max3_f32 v175, v51, v52, v53
	v_max3_f32 v176, v54, v55, v56
	v_max3_f32 v174, v174, v57, v58
	v_max3_f32 v175, v175, v59, v60
	v_max3_f32 v176, v176, v61, v62
	v_max3_f32 v174, v174, v175, v176
	v_max3_f32 v160, v160, v174, v63
	v_mov_b32_e32 v174, v160
	s_nop 1
	v_permlane32_swap_b32_e32 v174, v160
	s_andn2_b64 vcc, exec, s[48:49]
	v_max_f32_e32 v160, v160, v174
	s_andn2_b64 s[4:5], exec, s[48:49]
	s_mov_b64 s[48:49], -1
	s_cbranch_vccnz .LBB0_1345
	v_cmp_lt_f32_e32 vcc, s72, v160
	s_cbranch_vccz .LBB0_1349
	v_max_f32_e32 v160, v160, v160
	v_max_f32_e32 v160, 0, v160

.LBB0_1349:
	v_exp_f32_e32 v174, v64
	v_exp_f32_e32 v176, v65
	v_exp_f32_e32 v182, v66
	v_exp_f32_e32 v184, v67
	v_exp_f32_e32 v68, v68
	v_exp_f32_e32 v186, v69
	v_exp_f32_e32 v70, v70
	v_exp_f32_e32 v188, v71
	v_cvt_pk_bf16_f32 v64, v174, v176
	v_cvt_pk_bf16_f32 v65, v182, v184
	v_cvt_pk_bf16_f32 v66, v68, v186
	v_cvt_pk_bf16_f32 v67, v70, v188
	v_exp_f32_e32 v72, v72
	v_exp_f32_e32 v190, v73
	s_waitcnt lgkmcnt(0)
	v_mfma_f32_32x32x16_bf16 v[32:47], v[140:143], v[64:67], v[32:47]
	v_exp_f32_e32 v74, v74
	v_exp_f32_e32 v192, v75
	v_exp_f32_e32 v76, v76
	v_exp_f32_e32 v140, v77
	v_exp_f32_e32 v78, v78
	v_exp_f32_e32 v142, v79
	v_exp_f32_e32 v175, v48
	v_mfma_f32_32x32x16_bf16 v[16:31], v[136:139], v[64:67], v[16:31]
	v_exp_f32_e32 v177, v49
	v_exp_f32_e32 v183, v50
	v_exp_f32_e32 v185, v51
	v_cvt_pk_bf16_f32 v48, v72, v190
	v_cvt_pk_bf16_f32 v49, v74, v192
	v_cvt_pk_bf16_f32 v50, v76, v140
	v_cvt_pk_bf16_f32 v51, v78, v142
	v_exp_f32_e32 v69, v52
	v_exp_f32_e32 v187, v53
	v_mfma_f32_32x32x16_bf16 v[32:47], v[132:135], v[48:51], v[32:47]
	v_exp_f32_e32 v71, v54
	v_exp_f32_e32 v189, v55
	v_add_f32_e64 v52, v174, 0
	v_add_f32_e64 v53, v175, 0
	v_exp_f32_e32 v73, v56
	v_add_f32_e32 v52, v176, v52
	v_add_f32_e32 v53, v177, v53
	v_exp_f32_e32 v191, v57
	v_add_f32_e32 v52, v182, v52
	v_add_f32_e32 v53, v183, v53
	v_mfma_f32_32x32x16_bf16 v[16:31], v[128:131], v[48:51], v[16:31]
	v_cvt_pk_bf16_f32 v48, v175, v177
	v_cvt_pk_bf16_f32 v49, v183, v185
	v_cvt_pk_bf16_f32 v50, v69, v187
	v_cvt_pk_bf16_f32 v51, v71, v189
	v_add_f32_e64 v56, v184, v52
	v_add_f32_e64 v57, v185, v53
	v_exp_f32_e32 v75, v58
	v_exp_f32_e32 v193, v59
	v_mfma_f32_32x32x16_bf16 v[32:47], v[124:127], v[48:51], v[32:47]
	v_exp_f32_e32 v77, v60
	v_exp_f32_e32 v141, v61
	v_exp_f32_e32 v79, v62
	v_exp_f32_e32 v143, v63
	v_cvt_pk_bf16_f32 v52, v73, v191
	v_cvt_pk_bf16_f32 v53, v75, v193
	v_cvt_pk_bf16_f32 v54, v77, v141
	v_mfma_f32_32x32x16_bf16 v[16:31], v[120:123], v[48:51], v[16:31]
	v_add_f32_e64 v48, v68, v56
	v_add_f32_e64 v49, v69, v57
	v_cvt_pk_bf16_f32 v55, v79, v143
	v_add_f32_e64 v48, v186, v48
	v_add_f32_e64 v49, v187, v49
	s_mov_b64 s[4:5], 0
	v_add_f32_e32 v48, v70, v48
	v_add_f32_e32 v49, v71, v49
	s_nop 0
	v_add_f32_e32 v48, v188, v48
	v_add_f32_e32 v49, v189, v49
	v_mfma_f32_32x32x16_bf16 v[32:47], v[116:119], v[52:55], v[32:47]
	v_add_f32_e64 v48, v72, v48
	v_add_f32_e64 v49, v73, v49
	v_add_f32_e64 v48, v190, v48
	v_add_f32_e64 v49, v191, v49
	v_add_f32_e64 v48, v74, v48
	v_add_f32_e64 v49, v75, v49
	v_add_f32_e32 v48, v192, v48
	v_add_f32_e32 v49, v193, v49
	v_mfma_f32_32x32x16_bf16 v[16:31], v[112:115], v[52:55], v[16:31]
	v_add_f32_e64 v48, v76, v48
	v_add_f32_e64 v49, v77, v49
	v_add_f32_e64 v48, v140, v48
	v_add_f32_e64 v49, v141, v49
	v_add_f32_e64 v48, v78, v48
	v_add_f32_e64 v49, v79, v49
	v_add_f32_e32 v48, v142, v48
	v_add_f32_e32 v49, v143, v49
	s_nop 0
	v_add_f32_e32 v48, v48, v49
	v_add_f32_e32 v164, v164, v48
